# v12 + FF2B split-K cut 1792 | 2304 instead of 2048 | 2048: the split-0 half finishes its K-loop first and streams its in-place epilogue while the split-1 half is still in its K-loop
# speedup vs baseline: 1.0181x; 1.0054x over previous
.LBB0_1324:
	v_ashrrev_i32_e32 v1, 31, v8
	v_lshrrev_b32_e32 v1, 26, v1
	v_add_u32_e32 v1, v8, v1
	v_ashrrev_i32_e32 v9, 6, v1
	v_bfe_i32 v1, v8, 27, 1
	v_lshlrev_b32_e32 v0, 4, v8
	v_lshrrev_b32_e32 v1, 22, v1
	v_add_u32_e32 v1, v0, v1
	v_and_b32_e32 v1, 0xfffffc00, v1
	v_sub_u32_e32 v1, v0, v1
	v_lshrrev_b32_e32 v2, 4, v1
	v_bitop3_b32 v1, v2, v1, 32 bitop3:0x6c
	v_ashrrev_i32_e32 v3, 31, v1
	v_lshrrev_b32_e32 v3, 26, v3
	v_add_u32_e32 v3, v1, v3
	v_lshlrev_b32_e32 v2, 3, v9
	v_ashrrev_i32_e32 v10, 6, v3
	v_and_b32_e32 v3, 0xc0, v3
	v_and_b32_e32 v2, -16, v2
	v_sub_u32_e32 v1, v1, v3
	v_mov_b32_e32 v3, 1
	v_add_u32_e32 v2, v10, v2
	v_ashrrev_i16_sdwa v1, v3, sext(v1) dst_sel:DWORD dst_unused:UNUSED_PAD src0_sel:DWORD src1_sel:BYTE_0
	v_lshlrev_b32_e32 v4, 5, v9
	v_bfe_i32 v11, v1, 0, 16
	v_lshlrev_b32_e32 v1, 1, v2
	v_lshrrev_b32_e32 v5, 2, v2
	v_and_b32_e32 v6, 3, v10
	s_mov_b32 s12, 0x7ffe0
	v_and_b32_e32 v4, 32, v4
	v_and_b32_e32 v1, 24, v1
	v_and_b32_e32 v5, 4, v5
	v_and_or_b32 v6, v2, s12, v6
	v_or3_b32 v1, v6, v5, v1
	v_add_lshl_u32 v4, v4, v11, 1
	v_add_u32_e32 v0, 0x2000, v0
	v_lshl_add_u32 v162, v1, 13, v4
	v_ashrrev_i32_e32 v1, 31, v0
	v_lshrrev_b32_e32 v1, 22, v1
	v_add_u32_e32 v1, v0, v1
	v_ashrrev_i32_e32 v12, 10, v1
	v_mul_i32_i24_e32 v1, 0x400, v12
	v_sub_u32_e32 v0, v0, v1
	v_lshrrev_b32_e32 v1, 4, v0
	v_bitop3_b32 v0, v1, v0, 32 bitop3:0x6c
	s_waitcnt lgkmcnt(0)
	s_add_u32 s44, s10, 0x5800000
	v_lshl_add_u32 v160, v2, 13, v4
	v_ashrrev_i32_e32 v2, 31, v0
	s_addc_u32 s45, s11, 0
	v_lshrrev_b32_e32 v2, 26, v2
	s_add_u32 s48, s10, 0x2000000
	v_add_u32_e32 v2, v0, v2
	s_addc_u32 s49, s11, 0
	v_lshlrev_b32_e32 v1, 3, v12
	v_ashrrev_i32_e32 v13, 6, v2
	v_and_b32_e32 v2, 0xc0, v2
	s_add_i32 s7, s7, s5
	v_and_b32_e32 v1, -16, v1
	v_sub_u32_e32 v0, v0, v2
	s_ashr_i32 s5, s7, 31
	v_add_u32_e32 v1, v13, v1
	v_ashrrev_i16_sdwa v0, v3, sext(v0) dst_sel:DWORD dst_unused:UNUSED_PAD src0_sel:DWORD src1_sel:BYTE_0
	v_and_b32_e32 v3, 3, v13
	s_lshr_b32 s5, s5, 27
	v_and_or_b32 v3, v1, s12, v3
	s_add_i32 s12, s7, s5
	s_ashr_i32 s5, s12, 5
	s_lshl_b32 s13, s5, 3
	v_lshlrev_b32_e32 v4, 5, v12
	v_bfe_i32 v14, v0, 0, 16
	v_lshlrev_b32_e32 v0, 1, v1
	v_lshrrev_b32_e32 v2, 2, v1
	s_sub_i32 s5, 32, s13
	v_and_b32_e32 v4, 32, v4
	v_and_b32_e32 v0, 24, v0
	v_and_b32_e32 v2, 4, v2
	s_min_i32 s15, s5, 8
	v_or3_b32 v0, v3, v2, v0
	v_add_lshl_u32 v2, v4, v14, 1
	s_abs_i32 s16, s15
	v_lshl_add_u32 v164, v1, 13, v2
	v_cvt_f32_u32_e32 v1, s16
	v_lshl_add_u32 v166, v0, 13, v2
	s_sub_i32 s18, 0, s16
	s_andn2_b32 s12, s12, 31
	v_rcp_iflag_f32_e32 v0, v1
	s_sub_i32 s7, s7, s12
	s_abs_i32 s17, s7
	s_ashr_i32 s5, s6, 6
	v_mul_f32_e32 v0, 0x4f7ffffe, v0
	v_cvt_u32_f32_e32 v0, v0
	s_xor_b32 s12, s7, s15
	s_ashr_i32 s4, s6, 8
	s_lshl_b32 s50, s5, 10
	v_readfirstlane_b32 s19, v0
	s_mul_i32 s18, s18, s19
	s_mul_hi_u32 s18, s19, s18
	s_add_i32 s19, s19, s18
	s_mul_hi_u32 s18, s17, s19
	s_mul_i32 s19, s18, s16
	s_sub_i32 s17, s17, s19
	s_ashr_i32 s12, s12, 31
	s_add_i32 s19, s18, 1
	s_sub_i32 s20, s17, s16
	s_cmp_ge_u32 s17, s16
	s_cselect_b32 s18, s19, s18
	s_cselect_b32 s17, s20, s17
	s_add_i32 s19, s18, 1
	s_cmp_ge_u32 s17, s16
	s_cselect_b32 s16, s19, s18
	s_xor_b32 s16, s16, s12
	s_sub_i32 s22, s16, s12
	s_mul_i32 s12, s22, s15
	s_sub_i32 s7, s7, s12
	s_add_i32 s36, s13, s7
	s_ashr_i32 s37, s36, 31
	s_ashr_i32 s15, s14, 31
	s_ashr_i32 s23, s22, 31
	s_lshl_b64 s[12:13], s[36:37], 21
	s_lshl_b64 s[16:17], s[14:15], 12
	s_mov_b32 s98, 28
	s_mov_b32 s99, 29
	s_cmp_eq_u32 s56, 0x100
	s_cbranch_scc0 .Lff2b_even
	s_mul_i32 s16, s14, 0xe00
	s_mov_b32 s17, 0
	s_lshl_b32 s98, s14, 3
	s_add_i32 s99, s98, 25
	s_add_i32 s98, s98, 24
.Lff2b_even:
	s_lshl_b64 s[18:19], s[22:23], 21
	s_add_u32 s7, s48, s18
	s_addc_u32 s15, s49, s19
	s_add_u32 s40, s7, s16
	s_addc_u32 s41, s15, s17
	s_add_i32 s23, s50, 0
	s_add_i32 m0, s23, 0x10000
	v_mov_b32_e32 v163, 0
	global_load_lds_dwordx4 v162, s[40:41]
	s_add_i32 m0, s23, 0x12000
	s_add_u32 s7, s44, s12
	s_addc_u32 s15, s45, s13
	s_add_u32 s12, s40, 0x100000
	global_load_lds_dwordx4 v166, s[40:41]
	s_addc_u32 s13, s41, 0
	s_add_i32 m0, s23, 0x14000
	v_mov_b32_e32 v167, v163
	global_load_lds_dwordx4 v162, s[12:13]
	s_add_i32 m0, s23, 0x16000
	s_add_u32 s38, s7, s16
	s_addc_u32 s39, s15, s17
	s_add_i32 s37, s23, 0x2000
	global_load_lds_dwordx4 v166, s[12:13]
	s_mov_b32 m0, s23
	s_add_u32 s12, s38, 0x100000
	global_load_lds_dwordx4 v160, s[38:39]
	s_mov_b32 m0, s37
	s_addc_u32 s13, s39, 0
	s_add_i32 s51, s23, 0x4000
	global_load_lds_dwordx4 v164, s[38:39]
	s_mov_b32 m0, s51
	s_add_i32 s52, s23, 0x6000
	global_load_lds_dwordx4 v160, s[12:13]
	s_mov_b32 m0, s52
	v_mov_b32_e32 v161, v163
	global_load_lds_dwordx4 v164, s[12:13]
	s_load_dwordx2 s[12:13], s[0:1], 0xf0
	v_mov_b32_e32 v165, v163
	s_cmp_eq_u32 s4, 1
	s_mov_b32 s15, 0
	v_lshl_add_u64 v[6:7], s[40:41], 0, v[162:163]
	v_lshl_add_u64 v[4:5], s[40:41], 0, v[166:167]
	v_lshl_add_u64 v[0:1], s[38:39], 0, v[160:161]
	s_cselect_b64 s[16:17], -1, 0
	s_cmp_lg_u32 s4, 1
	v_lshl_add_u64 v[2:3], s[38:39], 0, v[164:165]
	s_cbranch_scc1 .LBB0_1326
	s_barrier

.LBB0_1340:
	ds_read_b128 v[128:131], v187
	ds_read_b128 v[132:135], v187 offset:1024
	ds_read_b128 v[136:139], v187 offset:2048
	ds_read_b128 v[140:143], v187 offset:3072
	ds_read_b128 v[144:147], v188
	ds_read_b128 v[148:151], v188 offset:1024
	ds_read_b128 v[152:155], v188 offset:2048
	ds_read_b128 v[156:159], v188 offset:3072
	s_add_u32 s40, s38, 0xfff00080
	s_addc_u32 s41, s39, -1
	s_cmp_eq_u32 s31, s98
	s_cselect_b32 s43, s7, s41
	s_cselect_b32 s42, s6, s40
	s_cselect_b32 s41, s35, s29
	s_cselect_b32 s40, s34, s27
	v_lshl_add_u64 v[214:215], s[38:39], 0, v[168:169]
	s_add_i32 m0, s23, 0xc000
	ds_read_b128 v[176:179], v189
	ds_read_b128 v[180:183], v189 offset:1024
	ds_read_b128 v[190:193], v189 offset:2048
	ds_read_b128 v[194:197], v189 offset:3072
	ds_read_b128 v[198:201], v189 offset:4096
	ds_read_b128 v[202:205], v189 offset:5120
	ds_read_b128 v[206:209], v189 offset:6144
	ds_read_b128 v[210:213], v189 offset:7168
	global_load_lds_dwordx4 v[214:215], off
	v_lshl_add_u64 v[214:215], s[38:39], 0, v[170:171]
	s_add_i32 m0, s23, 0xe000
	s_nop 0
	global_load_lds_dwordx4 v[214:215], off
	s_waitcnt vmcnt(8)
	s_waitcnt lgkmcnt(0)
	s_barrier
	s_setprio 1
	s_waitcnt lgkmcnt(0)
	v_mfma_f32_16x16x32_bf16 v[124:127], v[128:131], v[176:179], v[124:127]
	v_mfma_f32_16x16x32_bf16 v[120:123], v[136:139], v[176:179], v[120:123]
	v_mfma_f32_16x16x32_bf16 v[116:119], v[128:131], v[190:193], v[116:119]
	v_mfma_f32_16x16x32_bf16 v[112:115], v[136:139], v[190:193], v[112:115]
	v_mfma_f32_16x16x32_bf16 v[104:107], v[128:131], v[198:201], v[104:107]
	v_mfma_f32_16x16x32_bf16 v[96:99], v[136:139], v[198:201], v[96:99]
	v_mfma_f32_16x16x32_bf16 v[88:91], v[128:131], v[206:209], v[88:91]
	v_mfma_f32_16x16x32_bf16 v[80:83], v[136:139], v[206:209], v[80:83]
	v_mfma_f32_16x16x32_bf16 v[124:127], v[132:135], v[180:183], v[124:127]
	v_mfma_f32_16x16x32_bf16 v[120:123], v[140:143], v[180:183], v[120:123]
	v_mfma_f32_16x16x32_bf16 v[116:119], v[132:135], v[194:197], v[116:119]
	v_mfma_f32_16x16x32_bf16 v[112:115], v[140:143], v[194:197], v[112:115]
	v_mfma_f32_16x16x32_bf16 v[104:107], v[132:135], v[202:205], v[104:107]
	v_mfma_f32_16x16x32_bf16 v[96:99], v[140:143], v[202:205], v[96:99]
	v_mfma_f32_16x16x32_bf16 v[88:91], v[132:135], v[210:213], v[88:91]
	v_mfma_f32_16x16x32_bf16 v[80:83], v[140:143], v[210:213], v[80:83]
	s_setprio 0
	s_setprio 1
	v_mfma_f32_16x16x32_bf16 v[108:111], v[144:147], v[176:179], v[108:111]
	v_mfma_f32_16x16x32_bf16 v[100:103], v[152:155], v[176:179], v[100:103]
	v_mfma_f32_16x16x32_bf16 v[92:95], v[144:147], v[190:193], v[92:95]
	v_mfma_f32_16x16x32_bf16 v[84:87], v[152:155], v[190:193], v[84:87]
	v_mfma_f32_16x16x32_bf16 v[76:79], v[144:147], v[198:201], v[76:79]
	v_mfma_f32_16x16x32_bf16 v[72:75], v[152:155], v[198:201], v[72:75]
	v_mfma_f32_16x16x32_bf16 v[68:71], v[144:147], v[206:209], v[68:71]
	v_mfma_f32_16x16x32_bf16 v[64:67], v[152:155], v[206:209], v[64:67]
	v_mfma_f32_16x16x32_bf16 v[108:111], v[148:151], v[180:183], v[108:111]
	v_mfma_f32_16x16x32_bf16 v[100:103], v[156:159], v[180:183], v[100:103]
	v_mfma_f32_16x16x32_bf16 v[92:95], v[148:151], v[194:197], v[92:95]
	v_mfma_f32_16x16x32_bf16 v[84:87], v[156:159], v[194:197], v[84:87]
	v_mfma_f32_16x16x32_bf16 v[76:79], v[148:151], v[202:205], v[76:79]
	v_mfma_f32_16x16x32_bf16 v[72:75], v[156:159], v[202:205], v[72:75]
	v_mfma_f32_16x16x32_bf16 v[68:71], v[148:151], v[210:213], v[68:71]
	v_mfma_f32_16x16x32_bf16 v[64:67], v[156:159], v[210:213], v[64:67]
	s_setprio 0
	s_barrier
	s_add_i32 s46, s65, s50
	v_lshl_add_u64 v[214:215], s[40:41], 0, v[162:163]
	s_mov_b32 m0, s46
	ds_read_b128 v[176:179], v189 offset:16384
	ds_read_b128 v[180:183], v189 offset:17408
	ds_read_b128 v[190:193], v189 offset:18432
	ds_read_b128 v[194:197], v189 offset:19456
	ds_read_b128 v[198:201], v189 offset:20480
	ds_read_b128 v[202:205], v189 offset:21504
	ds_read_b128 v[206:209], v189 offset:22528
	ds_read_b128 v[210:213], v189 offset:23552
	global_load_lds_dwordx4 v[214:215], off
	s_add_i32 m0, s46, 0x2000
	s_add_u32 s46, s40, 0x100000
	v_lshl_add_u64 v[216:217], s[40:41], 0, v[166:167]
	s_addc_u32 s47, s41, 0
	s_add_i32 s60, s66, s50
	global_load_lds_dwordx4 v[216:217], off
	v_lshl_add_u64 v[218:219], s[46:47], 0, v[162:163]
	s_mov_b32 m0, s60
	v_lshl_add_u64 v[220:221], s[42:43], 0, v[164:165]
	global_load_lds_dwordx4 v[218:219], off
	v_lshl_add_u64 v[218:219], s[46:47], 0, v[166:167]
	s_add_i32 m0, s60, 0x2000
	s_nop 0
	global_load_lds_dwordx4 v[218:219], off
	v_lshl_add_u64 v[218:219], s[42:43], 0, v[160:161]
	s_waitcnt vmcnt(6)
	s_waitcnt lgkmcnt(0)
	s_barrier
	s_setprio 1
	s_waitcnt lgkmcnt(0)
	v_mfma_f32_16x16x32_bf16 v[60:63], v[128:131], v[176:179], v[60:63]
	v_mfma_f32_16x16x32_bf16 v[56:59], v[136:139], v[176:179], v[56:59]
	v_mfma_f32_16x16x32_bf16 v[52:55], v[128:131], v[190:193], v[52:55]
	v_mfma_f32_16x16x32_bf16 v[48:51], v[136:139], v[190:193], v[48:51]
	v_mfma_f32_16x16x32_bf16 v[40:43], v[128:131], v[198:201], v[40:43]
	v_mfma_f32_16x16x32_bf16 v[32:35], v[136:139], v[198:201], v[32:35]
	v_mfma_f32_16x16x32_bf16 v[24:27], v[128:131], v[206:209], v[24:27]
	v_mfma_f32_16x16x32_bf16 v[16:19], v[136:139], v[206:209], v[16:19]
	v_mfma_f32_16x16x32_bf16 v[60:63], v[132:135], v[180:183], v[60:63]
	v_mfma_f32_16x16x32_bf16 v[56:59], v[140:143], v[180:183], v[56:59]
	v_mfma_f32_16x16x32_bf16 v[52:55], v[132:135], v[194:197], v[52:55]
	v_mfma_f32_16x16x32_bf16 v[48:51], v[140:143], v[194:197], v[48:51]
	v_mfma_f32_16x16x32_bf16 v[40:43], v[132:135], v[202:205], v[40:43]
	v_mfma_f32_16x16x32_bf16 v[32:35], v[140:143], v[202:205], v[32:35]
	v_mfma_f32_16x16x32_bf16 v[24:27], v[132:135], v[210:213], v[24:27]
	v_mfma_f32_16x16x32_bf16 v[16:19], v[140:143], v[210:213], v[16:19]
	s_setprio 0
	s_setprio 1
	v_mfma_f32_16x16x32_bf16 v[44:47], v[144:147], v[176:179], v[44:47]
	v_mfma_f32_16x16x32_bf16 v[36:39], v[152:155], v[176:179], v[36:39]
	v_mfma_f32_16x16x32_bf16 v[28:31], v[144:147], v[190:193], v[28:31]
	v_mfma_f32_16x16x32_bf16 v[20:23], v[152:155], v[190:193], v[20:23]
	v_mfma_f32_16x16x32_bf16 v[12:15], v[144:147], v[198:201], v[12:15]
	v_mfma_f32_16x16x32_bf16 v[8:11], v[152:155], v[198:201], v[8:11]
	v_mfma_f32_16x16x32_bf16 v[4:7], v[144:147], v[206:209], v[4:7]
	v_mfma_f32_16x16x32_bf16 v[0:3], v[152:155], v[206:209], v[0:3]
	v_mfma_f32_16x16x32_bf16 v[44:47], v[148:151], v[180:183], v[44:47]
	v_mfma_f32_16x16x32_bf16 v[36:39], v[156:159], v[180:183], v[36:39]
	v_mfma_f32_16x16x32_bf16 v[28:31], v[148:151], v[194:197], v[28:31]
	v_mfma_f32_16x16x32_bf16 v[20:23], v[156:159], v[194:197], v[20:23]
	v_mfma_f32_16x16x32_bf16 v[12:15], v[148:151], v[202:205], v[12:15]
	v_mfma_f32_16x16x32_bf16 v[8:11], v[156:159], v[202:205], v[8:11]
	v_mfma_f32_16x16x32_bf16 v[4:7], v[148:151], v[210:213], v[4:7]
	v_mfma_f32_16x16x32_bf16 v[0:3], v[156:159], v[210:213], v[0:3]
	s_setprio 0
	s_barrier
	s_add_i32 s46, 0, 0x18000
	s_add_i32 s47, 0, 0x1c000
	v_add_u32_e32 v140, s46, v186
	v_add_u32_e32 v156, s47, v186
	ds_read_b128 v[128:131], v140
	ds_read_b128 v[132:135], v140 offset:1024
	ds_read_b128 v[136:139], v140 offset:2048
	ds_read_b128 v[140:143], v140 offset:3072
	ds_read_b128 v[144:147], v156
	ds_read_b128 v[148:151], v156 offset:1024
	ds_read_b128 v[152:155], v156 offset:2048
	ds_read_b128 v[156:159], v156 offset:3072
	s_add_u32 s42, s42, 0x100000
	s_addc_u32 s43, s43, 0
	s_mov_b32 m0, s51
	v_lshl_add_u64 v[222:223], s[42:43], 0, v[160:161]
	ds_read_b128 v[176:179], v189 offset:32768
	ds_read_b128 v[180:183], v189 offset:33792
	ds_read_b128 v[190:193], v189 offset:34816
	ds_read_b128 v[194:197], v189 offset:35840
	ds_read_b128 v[198:201], v189 offset:36864
	ds_read_b128 v[202:205], v189 offset:37888
	ds_read_b128 v[206:209], v189 offset:38912
	ds_read_b128 v[210:213], v189 offset:39936
	s_mov_b32 m0, s23
	s_nop 0
	global_load_lds_dwordx4 v[218:219], off
	s_mov_b32 m0, s37
	s_nop 0
	global_load_lds_dwordx4 v[220:221], off
	s_mov_b32 m0, s51
	s_nop 0
	global_load_lds_dwordx4 v[222:223], off
	v_lshl_add_u64 v[222:223], s[42:43], 0, v[164:165]
	s_mov_b32 m0, s52
	s_nop 0
	global_load_lds_dwordx4 v[222:223], off
	s_waitcnt vmcnt(8)
	s_waitcnt lgkmcnt(0)
	s_barrier
	s_setprio 1
	s_waitcnt lgkmcnt(0)
	v_mfma_f32_16x16x32_bf16 v[124:127], v[128:131], v[176:179], v[124:127]
	v_mfma_f32_16x16x32_bf16 v[120:123], v[136:139], v[176:179], v[120:123]
	v_mfma_f32_16x16x32_bf16 v[116:119], v[128:131], v[190:193], v[116:119]
	v_mfma_f32_16x16x32_bf16 v[112:115], v[136:139], v[190:193], v[112:115]
	v_mfma_f32_16x16x32_bf16 v[104:107], v[128:131], v[198:201], v[104:107]
	v_mfma_f32_16x16x32_bf16 v[96:99], v[136:139], v[198:201], v[96:99]
	v_mfma_f32_16x16x32_bf16 v[88:91], v[128:131], v[206:209], v[88:91]
	v_mfma_f32_16x16x32_bf16 v[80:83], v[136:139], v[206:209], v[80:83]
	v_mfma_f32_16x16x32_bf16 v[124:127], v[132:135], v[180:183], v[124:127]
	v_mfma_f32_16x16x32_bf16 v[120:123], v[140:143], v[180:183], v[120:123]
	v_mfma_f32_16x16x32_bf16 v[116:119], v[132:135], v[194:197], v[116:119]
	v_mfma_f32_16x16x32_bf16 v[112:115], v[140:143], v[194:197], v[112:115]
	v_mfma_f32_16x16x32_bf16 v[104:107], v[132:135], v[202:205], v[104:107]
	v_mfma_f32_16x16x32_bf16 v[96:99], v[140:143], v[202:205], v[96:99]
	v_mfma_f32_16x16x32_bf16 v[88:91], v[132:135], v[210:213], v[88:91]
	v_mfma_f32_16x16x32_bf16 v[80:83], v[140:143], v[210:213], v[80:83]
	s_setprio 0
	s_setprio 1
	v_mfma_f32_16x16x32_bf16 v[108:111], v[144:147], v[176:179], v[108:111]
	v_mfma_f32_16x16x32_bf16 v[100:103], v[152:155], v[176:179], v[100:103]
	v_mfma_f32_16x16x32_bf16 v[92:95], v[144:147], v[190:193], v[92:95]
	v_mfma_f32_16x16x32_bf16 v[84:87], v[152:155], v[190:193], v[84:87]
	v_mfma_f32_16x16x32_bf16 v[76:79], v[144:147], v[198:201], v[76:79]
	v_mfma_f32_16x16x32_bf16 v[72:75], v[152:155], v[198:201], v[72:75]
	v_mfma_f32_16x16x32_bf16 v[68:71], v[144:147], v[206:209], v[68:71]
	v_mfma_f32_16x16x32_bf16 v[64:67], v[152:155], v[206:209], v[64:67]
	v_mfma_f32_16x16x32_bf16 v[108:111], v[148:151], v[180:183], v[108:111]
	v_mfma_f32_16x16x32_bf16 v[100:103], v[156:159], v[180:183], v[100:103]
	v_mfma_f32_16x16x32_bf16 v[92:95], v[148:151], v[194:197], v[92:95]
	v_mfma_f32_16x16x32_bf16 v[84:87], v[156:159], v[194:197], v[84:87]
	v_mfma_f32_16x16x32_bf16 v[76:79], v[148:151], v[202:205], v[76:79]
	v_mfma_f32_16x16x32_bf16 v[72:75], v[156:159], v[202:205], v[72:75]
	v_mfma_f32_16x16x32_bf16 v[68:71], v[148:151], v[210:213], v[68:71]
	v_mfma_f32_16x16x32_bf16 v[64:67], v[156:159], v[210:213], v[64:67]
	s_setprio 0
	s_barrier
	s_add_i32 s42, s46, s50
	v_lshl_add_u64 v[214:215], v[214:215], 0, s[20:21]
	s_mov_b32 m0, s42
	ds_read_b128 v[176:179], v189 offset:49152
	ds_read_b128 v[180:183], v189 offset:50176
	ds_read_b128 v[190:193], v189 offset:51200
	ds_read_b128 v[194:197], v189 offset:52224
	ds_read_b128 v[198:201], v189 offset:53248
	ds_read_b128 v[202:205], v189 offset:54272
	ds_read_b128 v[206:209], v189 offset:55296
	ds_read_b128 v[210:213], v189 offset:56320
	global_load_lds_dwordx4 v[214:215], off
	s_add_i32 m0, s42, 0x2000
	s_add_u32 s40, s40, 0x100080
	v_lshl_add_u64 v[214:215], v[216:217], 0, s[20:21]
	s_addc_u32 s41, s41, 0
	s_add_i32 s42, s47, s50
	global_load_lds_dwordx4 v[214:215], off
	v_lshl_add_u64 v[214:215], s[40:41], 0, v[162:163]
	s_mov_b32 m0, s42
	s_nop 0
	global_load_lds_dwordx4 v[214:215], off
	v_lshl_add_u64 v[214:215], s[40:41], 0, v[166:167]
	s_add_i32 m0, s42, 0x2000
	s_nop 0
	global_load_lds_dwordx4 v[214:215], off
	v_lshl_add_u64 v[214:215], v[218:219], 0, s[20:21]
	s_mov_b32 m0, s55
	s_nop 0
	global_load_lds_dwordx4 v[214:215], off
	v_lshl_add_u64 v[214:215], v[220:221], 0, s[20:21]
	s_mov_b32 m0, s62
	s_nop 0
	global_load_lds_dwordx4 v[214:215], off
	s_waitcnt vmcnt(8)
	s_waitcnt lgkmcnt(0)
	s_barrier
	s_setprio 1
	s_waitcnt lgkmcnt(0)
	v_mfma_f32_16x16x32_bf16 v[60:63], v[128:131], v[176:179], v[60:63]
	v_mfma_f32_16x16x32_bf16 v[56:59], v[136:139], v[176:179], v[56:59]
	v_mfma_f32_16x16x32_bf16 v[52:55], v[128:131], v[190:193], v[52:55]
	v_mfma_f32_16x16x32_bf16 v[48:51], v[136:139], v[190:193], v[48:51]
	v_mfma_f32_16x16x32_bf16 v[40:43], v[128:131], v[198:201], v[40:43]
	v_mfma_f32_16x16x32_bf16 v[32:35], v[136:139], v[198:201], v[32:35]
	v_mfma_f32_16x16x32_bf16 v[24:27], v[128:131], v[206:209], v[24:27]
	v_mfma_f32_16x16x32_bf16 v[16:19], v[136:139], v[206:209], v[16:19]
	v_mfma_f32_16x16x32_bf16 v[60:63], v[132:135], v[180:183], v[60:63]
	v_mfma_f32_16x16x32_bf16 v[56:59], v[140:143], v[180:183], v[56:59]
	v_mfma_f32_16x16x32_bf16 v[52:55], v[132:135], v[194:197], v[52:55]
	v_mfma_f32_16x16x32_bf16 v[48:51], v[140:143], v[194:197], v[48:51]
	v_mfma_f32_16x16x32_bf16 v[40:43], v[132:135], v[202:205], v[40:43]
	v_mfma_f32_16x16x32_bf16 v[32:35], v[140:143], v[202:205], v[32:35]
	v_mfma_f32_16x16x32_bf16 v[24:27], v[132:135], v[210:213], v[24:27]
	v_mfma_f32_16x16x32_bf16 v[16:19], v[140:143], v[210:213], v[16:19]
	s_setprio 0
	s_setprio 1
	v_mfma_f32_16x16x32_bf16 v[44:47], v[144:147], v[176:179], v[44:47]
	v_mfma_f32_16x16x32_bf16 v[36:39], v[152:155], v[176:179], v[36:39]
	v_mfma_f32_16x16x32_bf16 v[28:31], v[144:147], v[190:193], v[28:31]
	v_mfma_f32_16x16x32_bf16 v[20:23], v[152:155], v[190:193], v[20:23]
	v_mfma_f32_16x16x32_bf16 v[12:15], v[144:147], v[198:201], v[12:15]
	v_mfma_f32_16x16x32_bf16 v[8:11], v[152:155], v[198:201], v[8:11]
	v_mfma_f32_16x16x32_bf16 v[4:7], v[144:147], v[206:209], v[4:7]
	v_mfma_f32_16x16x32_bf16 v[0:3], v[152:155], v[206:209], v[0:3]
	v_mfma_f32_16x16x32_bf16 v[44:47], v[148:151], v[180:183], v[44:47]
	v_mfma_f32_16x16x32_bf16 v[36:39], v[156:159], v[180:183], v[36:39]
	v_mfma_f32_16x16x32_bf16 v[28:31], v[148:151], v[194:197], v[28:31]
	v_mfma_f32_16x16x32_bf16 v[20:23], v[156:159], v[194:197], v[20:23]
	v_mfma_f32_16x16x32_bf16 v[12:15], v[148:151], v[202:205], v[12:15]
	v_mfma_f32_16x16x32_bf16 v[8:11], v[156:159], v[202:205], v[8:11]
	v_mfma_f32_16x16x32_bf16 v[4:7], v[148:151], v[210:213], v[4:7]
	v_mfma_f32_16x16x32_bf16 v[0:3], v[156:159], v[210:213], v[0:3]
	s_setprio 0
	s_barrier
	s_add_i32 s31, s31, 2
	s_add_u32 s38, s38, 0x100
	s_addc_u32 s39, s39, 0
	s_add_u32 s27, s27, 0x100
	s_addc_u32 s29, s29, 0
	s_cmp_gt_u32 s31, s99
	s_cbranch_scc0 .LBB0_1340
	s_and_b64 vcc, exec, s[24:25]
	s_cbranch_vccz .LBB0_1343
	s_barrier
